# merged consecutive lgkmcnt waits in MLA and dense attention loops (same-burst LDS reads waited once)
# speedup vs baseline: 1.0056x; 1.0056x over previous
.LBB0_441:
	s_and_b32 s48, s33, 2
	s_add_i32 s4, s33, -1
	s_and_b32 s49, s4, 3
	s_mul_i32 s4, s48, 0x4800
	v_add_u32_e32 v168, s4, v184
	s_cmp_eq_u32 s33, 0
	ds_read_b128 v[164:167], v168 offset:96
	s_cselect_b64 s[6:7], -1, 0
	s_mulk_i32 s49, 0x4800
	s_and_b64 s[4:5], s[6:7], exec
	s_cselect_b32 s4, 0, s49
	v_add_u32_e32 v84, s4, v184
	v_exp_f32_e32 v64, v64
	v_exp_f32_e32 v65, v65
	v_add_f32_e32 v85, 0, v64
	v_add_f32_e32 v113, v65, v85
	v_cvt_pk_bf16_f32 v112, v64, v65
	ds_read_b128 v[186:189], v84 offset:9280
	ds_read_b128 v[190:193], v84 offset:9312
	ds_read_b128 v[194:197], v84 offset:13888
	ds_read_b128 v[198:201], v84 offset:13920
	s_waitcnt lgkmcnt(7)
	v_mfma_f32_32x32x16_bf16 v[80:95], v[80:83], v[148:151], 0
	v_exp_f32_e32 v64, v66
	v_exp_f32_e32 v65, v67
	v_add_f32_e32 v66, v64, v113
	v_add_f32_e32 v66, v65, v66
	v_cvt_pk_bf16_f32 v113, v64, v65
	s_waitcnt lgkmcnt(6)
	v_mfma_f32_32x32x16_bf16 v[80:95], v[108:111], v[152:155], v[80:95]
	v_exp_f32_e32 v64, v68
	v_exp_f32_e32 v65, v69
	v_add_f32_e32 v66, v64, v66
	v_cvt_pk_bf16_f32 v114, v64, v65
	v_add_f32_e32 v64, v65, v66
	s_waitcnt lgkmcnt(5)
	v_mfma_f32_32x32x16_bf16 v[80:95], v[104:107], v[156:159], v[80:95]
	v_exp_f32_e32 v65, v70
	v_exp_f32_e32 v66, v71
	v_add_f32_e32 v64, v65, v64
	v_cvt_pk_bf16_f32 v115, v65, v66
	v_add_f32_e32 v64, v66, v64
	s_waitcnt lgkmcnt(4)
	v_mfma_f32_32x32x16_bf16 v[80:95], v[164:167], v[160:163], v[80:95]
	v_exp_f32_e32 v65, v72
	v_exp_f32_e32 v66, v73
	v_add_f32_e32 v64, v65, v64
	v_cvt_pk_bf16_f32 v104, v65, v66
	v_add_f32_e32 v64, v66, v64
	s_waitcnt lgkmcnt(0)
	v_mfma_f32_32x32x16_bf16 v[16:31], v[186:189], v[96:99], v[16:31]
	v_exp_f32_e32 v65, v74
	v_exp_f32_e32 v66, v75
	v_add_f32_e32 v64, v65, v64
	v_cvt_pk_bf16_f32 v105, v65, v66
	v_add_f32_e32 v64, v66, v64
	v_mfma_f32_32x32x16_bf16 v[16:31], v[190:193], v[100:103], v[16:31]
	v_exp_f32_e32 v65, v76
	v_exp_f32_e32 v66, v77
	v_add_f32_e32 v64, v65, v64
	v_cvt_pk_bf16_f32 v106, v65, v66
	v_add_f32_e32 v64, v66, v64
	v_mfma_f32_32x32x16_bf16 v[0:15], v[194:197], v[96:99], v[0:15]
	v_exp_f32_e32 v65, v78
	v_exp_f32_e32 v66, v79
	v_add_f32_e32 v64, v65, v64
	v_cvt_pk_bf16_f32 v107, v65, v66
	v_add_f32_e32 v185, v66, v64
	v_mfma_f32_32x32x16_bf16 v[0:15], v[198:201], v[100:103], v[0:15]
	ds_read_b128 v[64:67], v168 offset:4608
	ds_read_b128 v[164:167], v168 offset:4640
	ds_read_b128 v[108:111], v168 offset:4672
	v_cmp_ge_f32_e32 vcc, s62, v185
	s_mov_b64 s[8:9], -1
	s_mov_b64 s[4:5], -1
	s_and_saveexec_b64 s[10:11], vcc
	v_cmp_gt_f32_e32 vcc, s75, v185
	s_and_b64 s[4:5], s[6:7], vcc
	s_orn2_b64 s[4:5], s[4:5], exec
	s_or_b64 exec, exec, s[10:11]
	ds_read_b128 v[186:189], v168 offset:4704
	v_exp_f32_e32 v68, v80
	v_exp_f32_e32 v69, v81
	v_add_f32_e32 v70, 0, v68
	v_add_f32_e32 v80, v69, v70
	v_cvt_pk_bf16_f32 v96, v68, v69
	s_waitcnt lgkmcnt(3)
	v_mfma_f32_32x32x16_bf16 v[64:79], v[64:67], v[116:119], 0
	ds_read_b128 v[190:193], v168 offset:9216
	ds_read_b128 v[194:197], v168 offset:9248
	ds_read_b128 v[198:201], v168 offset:13824
	ds_read_b128 v[230:233], v168 offset:13856
	v_exp_f32_e32 v81, v82
	v_exp_f32_e32 v82, v83
	v_add_f32_e32 v80, v81, v80
	v_add_f32_e32 v80, v82, v80
	v_cvt_pk_bf16_f32 v97, v81, v82
	s_waitcnt lgkmcnt(5)
	v_mfma_f32_32x32x16_bf16 v[64:79], v[164:167], v[120:123], v[64:79]
	v_exp_f32_e32 v81, v84
	v_exp_f32_e32 v82, v85
	v_add_f32_e32 v80, v81, v80
	v_cvt_pk_bf16_f32 v98, v81, v82
	v_add_f32_e32 v80, v82, v80
	v_mfma_f32_32x32x16_bf16 v[64:79], v[108:111], v[124:127], v[64:79]
	v_exp_f32_e32 v81, v86
	v_exp_f32_e32 v82, v87
	v_add_f32_e32 v80, v81, v80
	v_cvt_pk_bf16_f32 v99, v81, v82
	v_add_f32_e32 v80, v82, v80
	s_waitcnt lgkmcnt(4)
	v_mfma_f32_32x32x16_bf16 v[64:79], v[186:189], v[128:131], v[64:79]
	v_exp_f32_e32 v81, v88
	v_exp_f32_e32 v82, v89
	v_add_f32_e32 v80, v81, v80
	v_cvt_pk_bf16_f32 v100, v81, v82
	v_add_f32_e32 v80, v82, v80
	s_waitcnt lgkmcnt(0)
	v_mfma_f32_32x32x16_bf16 v[48:63], v[190:193], v[112:115], v[48:63]
	v_exp_f32_e32 v81, v90
	v_exp_f32_e32 v82, v91
	v_add_f32_e32 v80, v81, v80
	v_cvt_pk_bf16_f32 v101, v81, v82
	v_add_f32_e32 v80, v82, v80
	v_mfma_f32_32x32x16_bf16 v[48:63], v[194:197], v[104:107], v[48:63]
	v_exp_f32_e32 v81, v92
	v_exp_f32_e32 v82, v93
	v_add_f32_e32 v80, v81, v80
	v_cvt_pk_bf16_f32 v102, v81, v82
	v_add_f32_e32 v80, v82, v80
	v_mfma_f32_32x32x16_bf16 v[32:47], v[198:201], v[112:115], v[32:47]
	v_exp_f32_e32 v81, v94
	v_exp_f32_e32 v82, v95
	v_add_f32_e32 v80, v81, v80
	v_cvt_pk_bf16_f32 v103, v81, v82
	v_add_f32_e32 v164, v82, v80
	v_mfma_f32_32x32x16_bf16 v[32:47], v[230:233], v[104:107], v[32:47]
	ds_read_b128 v[80:83], v168 offset:4608
	ds_read_b128 v[112:115], v168 offset:4640
	ds_read_b128 v[108:111], v168 offset:4672
	v_cndmask_b32_e64 v84, 0, 1, s[4:5]
	v_cmp_ne_u32_e64 s[4:5], 0, v84
	v_cmp_ge_f32_e32 vcc, s62, v164
	s_and_saveexec_b64 s[10:11], vcc
	v_cmp_gt_f32_e32 vcc, s75, v164
	s_and_b64 s[6:7], s[6:7], vcc
	s_orn2_b64 s[8:9], s[6:7], exec
	s_or_b64 exec, exec, s[10:11]
	v_cndmask_b32_e64 v84, 0, 1, s[8:9]
	v_cmp_ne_u32_e64 s[6:7], 0, v84
	ds_read_b128 v[104:107], v168 offset:4704
	v_exp_f32_e32 v64, v64
	v_exp_f32_e32 v65, v65
	v_add_f32_e32 v84, 0, v64
	v_add_f32_e32 v165, v65, v84
	v_cvt_pk_bf16_f32 v186, v64, v65
	s_waitcnt lgkmcnt(3)
	v_mfma_f32_32x32x16_bf16 v[80:95], v[80:83], v[148:151], 0
	ds_read_b128 v[190:193], v168 offset:9216
	ds_read_b128 v[194:197], v168 offset:9248
	ds_read_b128 v[198:201], v168 offset:13824
	ds_read_b128 v[230:233], v168 offset:13856
	v_exp_f32_e32 v64, v66
	v_exp_f32_e32 v65, v67
	v_add_f32_e32 v66, v64, v165
	v_add_f32_e32 v66, v65, v66
	v_cvt_pk_bf16_f32 v187, v64, v65
	s_waitcnt lgkmcnt(5)
	v_mfma_f32_32x32x16_bf16 v[80:95], v[112:115], v[152:155], v[80:95]
	v_exp_f32_e32 v64, v68
	v_exp_f32_e32 v65, v69
	v_add_f32_e32 v66, v64, v66
	v_cvt_pk_bf16_f32 v188, v64, v65
	v_add_f32_e32 v64, v65, v66
	v_mfma_f32_32x32x16_bf16 v[80:95], v[108:111], v[156:159], v[80:95]
	v_exp_f32_e32 v65, v70
	v_exp_f32_e32 v66, v71
	v_add_f32_e32 v64, v65, v64
	v_cvt_pk_bf16_f32 v189, v65, v66
	v_add_f32_e32 v64, v66, v64
	s_waitcnt lgkmcnt(4)
	v_mfma_f32_32x32x16_bf16 v[80:95], v[104:107], v[160:163], v[80:95]
	v_exp_f32_e32 v65, v72
	v_exp_f32_e32 v66, v73
	v_add_f32_e32 v64, v65, v64
	v_cvt_pk_bf16_f32 v108, v65, v66
	v_add_f32_e32 v64, v66, v64
	s_waitcnt lgkmcnt(0)
	v_mfma_f32_32x32x16_bf16 v[16:31], v[190:193], v[96:99], v[16:31]
	v_exp_f32_e32 v65, v74
	v_exp_f32_e32 v66, v75
	v_add_f32_e32 v64, v65, v64
	v_cvt_pk_bf16_f32 v109, v65, v66
	v_add_f32_e32 v64, v66, v64
	v_mfma_f32_32x32x16_bf16 v[16:31], v[194:197], v[100:103], v[16:31]
	v_exp_f32_e32 v65, v76
	v_exp_f32_e32 v66, v77
	v_add_f32_e32 v64, v65, v64
	v_cvt_pk_bf16_f32 v110, v65, v66
	v_add_f32_e32 v64, v66, v64
	v_mfma_f32_32x32x16_bf16 v[0:15], v[198:201], v[96:99], v[0:15]
	v_exp_f32_e32 v65, v78
	v_exp_f32_e32 v66, v79
	v_add_f32_e32 v64, v65, v64
	v_cvt_pk_bf16_f32 v111, v65, v66
	v_add_f32_e32 v104, v66, v64
	v_mfma_f32_32x32x16_bf16 v[0:15], v[230:233], v[100:103], v[0:15]
	ds_read_b128 v[64:67], v168 offset:18432
	ds_read_b128 v[96:99], v168 offset:18464
	ds_read_b128 v[112:115], v168 offset:18496
	v_cmp_nge_f32_e64 s[8:9], s62, v104
	ds_read_b128 v[100:103], v168 offset:18528
	v_exp_f32_e32 v68, v80
	v_exp_f32_e32 v69, v81
	v_add_f32_e32 v70, 0, v68
	v_add_f32_e32 v81, v69, v70
	v_cvt_pk_bf16_f32 v80, v68, v69
	s_waitcnt lgkmcnt(3)
	v_mfma_f32_32x32x16_bf16 v[64:79], v[64:67], v[116:119], 0
	ds_read_b128 v[190:193], v168 offset:9280
	ds_read_b128 v[194:197], v168 offset:9312
	ds_read_b128 v[198:201], v168 offset:13888
	ds_read_b128 v[230:233], v168 offset:13920
	v_exp_f32_e32 v82, v82
	v_exp_f32_e32 v83, v83
	v_add_f32_e32 v81, v82, v81
	v_add_f32_e32 v105, v83, v81
	v_cvt_pk_bf16_f32 v81, v82, v83
	s_waitcnt lgkmcnt(5)
	v_mfma_f32_32x32x16_bf16 v[64:79], v[96:99], v[120:123], v[64:79]
	v_exp_f32_e32 v82, v84
	v_exp_f32_e32 v83, v85
	v_add_f32_e32 v84, v82, v105
	v_cvt_pk_bf16_f32 v82, v82, v83
	v_add_f32_e32 v83, v83, v84
	v_mfma_f32_32x32x16_bf16 v[64:79], v[112:115], v[124:127], v[64:79]
	v_exp_f32_e32 v84, v86
	v_exp_f32_e32 v85, v87
	v_add_f32_e32 v86, v84, v83
	v_cvt_pk_bf16_f32 v83, v84, v85
	v_add_f32_e32 v84, v85, v86
	s_waitcnt lgkmcnt(4)
	v_mfma_f32_32x32x16_bf16 v[64:79], v[100:103], v[128:131], v[64:79]
	v_exp_f32_e32 v85, v88
	v_exp_f32_e32 v86, v89
	v_add_f32_e32 v87, v85, v84
	v_cvt_pk_bf16_f32 v84, v85, v86
	v_add_f32_e32 v85, v86, v87
	s_waitcnt lgkmcnt(0)
	v_mfma_f32_32x32x16_bf16 v[48:63], v[190:193], v[186:189], v[48:63]
	v_exp_f32_e32 v86, v90
	v_exp_f32_e32 v87, v91
	v_add_f32_e32 v88, v86, v85
	v_cvt_pk_bf16_f32 v85, v86, v87
	v_add_f32_e32 v86, v87, v88
	v_mfma_f32_32x32x16_bf16 v[48:63], v[194:197], v[108:111], v[48:63]
	v_exp_f32_e32 v87, v92
	v_exp_f32_e32 v88, v93
	v_add_f32_e32 v89, v87, v86
	v_cvt_pk_bf16_f32 v86, v87, v88
	v_add_f32_e32 v87, v88, v89
	v_mfma_f32_32x32x16_bf16 v[32:47], v[198:201], v[186:189], v[32:47]
	v_exp_f32_e32 v88, v94
	v_exp_f32_e32 v89, v95
	v_add_f32_e32 v90, v88, v87
	v_cvt_pk_bf16_f32 v87, v88, v89
	v_add_f32_e32 v105, v89, v90
	v_mfma_f32_32x32x16_bf16 v[32:47], v[230:233], v[108:111], v[32:47]
	ds_read_b128 v[96:99], v168 offset:18432
	ds_read_b128 v[92:95], v168 offset:18464
	ds_read_b128 v[88:91], v168 offset:18496
	v_cmp_nge_f32_e64 s[10:11], s62, v105
	s_waitcnt lgkmcnt(0)
	s_barrier
	s_cmpk_gt_u32 s33, 0xfc
	s_cbranch_scc1 .LBB0_447
	v_add_u32_e32 v100, s49, v173
	s_waitcnt vmcnt(1)
	ds_write_b128 v100, v[140:143]
	s_waitcnt vmcnt(0)
	ds_write_b128 v100, v[144:147] offset:9216

.LBB0_449:
	v_add_f32_e32 v101, v179, v164
	ds_read_b128 v[164:167], v168 offset:18528
	s_or_b64 s[4:5], s[6:7], s[4:5]
	v_add_f32_e32 v100, v178, v185
	s_or_b64 s[4:5], s[4:5], s[8:9]
	s_or_b64 s[4:5], s[4:5], s[10:11]
	v_pk_add_f32 v[182:183], v[100:101], v[104:105]
	s_xor_b32 s8, s48, 2
	v_exp_f32_e32 v64, v64
	v_exp_f32_e32 v65, v65
	v_add_f32_e32 v100, 0, v64
	v_add_f32_e32 v185, v65, v100
	v_cvt_pk_bf16_f32 v64, v64, v65
	s_waitcnt lgkmcnt(3)
	v_mfma_f32_32x32x16_bf16 v[100:115], v[96:99], v[148:151], 0
	ds_read_b128 v[178:181], v168 offset:9280
	ds_read_b128 v[186:189], v168 offset:9312
	ds_read_b128 v[190:193], v168 offset:13888
	ds_read_b128 v[194:197], v168 offset:13920
	v_exp_f32_e32 v65, v66
	v_exp_f32_e32 v66, v67
	v_add_f32_e32 v67, v65, v185
	v_add_f32_e32 v67, v66, v67
	v_cvt_pk_bf16_f32 v65, v65, v66
	s_waitcnt lgkmcnt(6)
	v_mfma_f32_32x32x16_bf16 v[100:115], v[92:95], v[152:155], v[100:115]
	v_exp_f32_e32 v66, v68
	v_exp_f32_e32 v68, v69
	v_add_f32_e32 v67, v66, v67
	v_cvt_pk_bf16_f32 v66, v66, v68
	v_add_f32_e32 v67, v68, v67
	s_waitcnt lgkmcnt(5)
	v_mfma_f32_32x32x16_bf16 v[100:115], v[88:91], v[156:159], v[100:115]
	v_exp_f32_e32 v68, v70
	v_exp_f32_e32 v69, v71
	v_add_f32_e32 v70, v68, v67
	v_cvt_pk_bf16_f32 v67, v68, v69
	v_add_f32_e32 v68, v69, v70
	s_waitcnt lgkmcnt(4)
	v_mfma_f32_32x32x16_bf16 v[100:115], v[164:167], v[160:163], v[100:115]
	v_exp_f32_e32 v69, v72
	v_exp_f32_e32 v70, v73
	v_add_f32_e32 v71, v69, v68
	v_cvt_pk_bf16_f32 v68, v69, v70
	v_add_f32_e32 v69, v70, v71
	s_waitcnt lgkmcnt(0)
	v_mfma_f32_32x32x16_bf16 v[16:31], v[178:181], v[80:83], v[16:31]
	v_exp_f32_e32 v70, v74
	v_exp_f32_e32 v71, v75
	v_add_f32_e32 v72, v70, v69
	v_cvt_pk_bf16_f32 v69, v70, v71
	v_add_f32_e32 v70, v71, v72
	v_mfma_f32_32x32x16_bf16 v[16:31], v[186:189], v[84:87], v[16:31]
	v_exp_f32_e32 v71, v76
	v_exp_f32_e32 v72, v77
	v_add_f32_e32 v73, v71, v70
	v_cvt_pk_bf16_f32 v70, v71, v72
	v_add_f32_e32 v71, v72, v73
	v_mfma_f32_32x32x16_bf16 v[0:15], v[190:193], v[80:83], v[0:15]
	v_exp_f32_e32 v72, v78
	v_exp_f32_e32 v73, v79
	v_add_f32_e32 v74, v72, v71
	v_cvt_pk_bf16_f32 v71, v72, v73
	v_add_f32_e32 v198, v73, v74
	v_mfma_f32_32x32x16_bf16 v[0:15], v[194:197], v[84:87], v[0:15]
	ds_read_b128 v[72:75], v168 offset:23040
	ds_read_b128 v[76:79], v168 offset:23072
	ds_read_b128 v[80:83], v168 offset:23104
	v_cmp_nge_f32_e32 vcc, s62, v198
	ds_read_b128 v[84:87], v168 offset:23136
	v_exp_f32_e32 v88, v100
	v_exp_f32_e32 v89, v101
	v_add_f32_e32 v90, 0, v88
	v_add_f32_e32 v165, v89, v90
	v_cvt_pk_bf16_f32 v164, v88, v89
	v_exp_f32_e32 v166, v102
	v_exp_f32_e32 v167, v103
	s_waitcnt lgkmcnt(3)
	v_mfma_f32_32x32x16_bf16 v[88:103], v[72:75], v[116:119], 0
	ds_read_b128 v[178:181], v168 offset:27648
	ds_read_b128 v[186:189], v168 offset:27680
	ds_read_b128 v[190:193], v168 offset:32256
	ds_read_b128 v[194:197], v168 offset:32288
	v_add_f32_e32 v72, v166, v165
	v_add_f32_e32 v72, v167, v72
	v_cvt_pk_bf16_f32 v165, v166, v167
	s_waitcnt lgkmcnt(5)
	v_mfma_f32_32x32x16_bf16 v[88:103], v[76:79], v[120:123], v[88:103]
	v_exp_f32_e32 v73, v104
	v_exp_f32_e32 v74, v105
	v_add_f32_e32 v72, v73, v72
	v_cvt_pk_bf16_f32 v166, v73, v74
	v_add_f32_e32 v72, v74, v72
	v_mfma_f32_32x32x16_bf16 v[88:103], v[80:83], v[124:127], v[88:103]
	v_exp_f32_e32 v73, v106
	v_exp_f32_e32 v74, v107
	v_add_f32_e32 v72, v73, v72
	v_cvt_pk_bf16_f32 v167, v73, v74
	v_add_f32_e32 v72, v74, v72
	s_waitcnt lgkmcnt(4)
	v_mfma_f32_32x32x16_bf16 v[88:103], v[84:87], v[128:131], v[88:103]
	v_exp_f32_e32 v73, v108
	v_exp_f32_e32 v74, v109
	v_add_f32_e32 v75, v73, v72
	v_cvt_pk_bf16_f32 v72, v73, v74
	v_add_f32_e32 v73, v74, v75
	s_waitcnt lgkmcnt(0)
	v_mfma_f32_32x32x16_bf16 v[48:63], v[178:181], v[64:67], v[48:63]
	v_exp_f32_e32 v74, v110
	v_exp_f32_e32 v75, v111
	v_add_f32_e32 v76, v74, v73
	v_cvt_pk_bf16_f32 v73, v74, v75
	v_add_f32_e32 v74, v75, v76
	v_mfma_f32_32x32x16_bf16 v[48:63], v[186:189], v[68:71], v[48:63]
	v_exp_f32_e32 v75, v112
	v_exp_f32_e32 v76, v113
	v_add_f32_e32 v77, v75, v74
	v_cvt_pk_bf16_f32 v74, v75, v76
	v_add_f32_e32 v75, v76, v77
	v_mfma_f32_32x32x16_bf16 v[32:47], v[190:193], v[64:67], v[32:47]
	v_exp_f32_e32 v76, v114
	v_exp_f32_e32 v77, v115
	v_add_f32_e32 v78, v76, v75
	v_cvt_pk_bf16_f32 v75, v76, v77
	v_add_f32_e32 v199, v77, v78
	v_mfma_f32_32x32x16_bf16 v[32:47], v[194:197], v[68:71], v[32:47]
	ds_read_b128 v[64:67], v168 offset:23040
	ds_read_b128 v[104:107], v168 offset:23072
	ds_read_b128 v[108:111], v168 offset:23104
	s_or_b64 s[6:7], s[4:5], vcc
	v_cmp_nge_f32_e32 vcc, s62, v199
	v_pk_add_f32 v[182:183], v[182:183], v[198:199]
	ds_read_b128 v[68:71], v168 offset:23136
	v_exp_f32_e32 v76, v88
	v_exp_f32_e32 v77, v89
	v_add_f32_e32 v78, 0, v76
	v_add_f32_e32 v113, v77, v78
	v_cvt_pk_bf16_f32 v112, v76, v77
	v_exp_f32_e32 v114, v90
	v_exp_f32_e32 v115, v91
	s_waitcnt lgkmcnt(3)
	v_mfma_f32_32x32x16_bf16 v[76:91], v[64:67], v[148:151], 0
	ds_read_b128 v[178:181], v168 offset:27648
	ds_read_b128 v[186:189], v168 offset:27680
	ds_read_b128 v[190:193], v168 offset:32256
	ds_read_b128 v[194:197], v168 offset:32288
	v_add_f32_e32 v64, v114, v113
	v_add_f32_e32 v64, v115, v64
	v_cvt_pk_bf16_f32 v113, v114, v115
	s_waitcnt lgkmcnt(5)
	v_mfma_f32_32x32x16_bf16 v[76:91], v[104:107], v[152:155], v[76:91]
	v_exp_f32_e32 v65, v92
	v_exp_f32_e32 v66, v93
	v_add_f32_e32 v64, v65, v64
	v_cvt_pk_bf16_f32 v114, v65, v66
	v_add_f32_e32 v64, v66, v64
	v_mfma_f32_32x32x16_bf16 v[76:91], v[108:111], v[156:159], v[76:91]
	v_exp_f32_e32 v65, v94
	v_exp_f32_e32 v66, v95
	v_add_f32_e32 v64, v65, v64
	v_cvt_pk_bf16_f32 v115, v65, v66
	v_add_f32_e32 v64, v66, v64
	s_waitcnt lgkmcnt(4)
	v_mfma_f32_32x32x16_bf16 v[76:91], v[68:71], v[160:163], v[76:91]
	v_exp_f32_e32 v65, v96
	v_exp_f32_e32 v66, v97
	v_add_f32_e32 v64, v65, v64
	v_cvt_pk_bf16_f32 v92, v65, v66
	v_add_f32_e32 v64, v66, v64
	s_waitcnt lgkmcnt(0)
	v_mfma_f32_32x32x16_bf16 v[16:31], v[178:181], v[164:167], v[16:31]
	v_exp_f32_e32 v65, v98
	v_exp_f32_e32 v66, v99
	v_add_f32_e32 v64, v65, v64
	v_cvt_pk_bf16_f32 v93, v65, v66
	v_add_f32_e32 v64, v66, v64
	v_mfma_f32_32x32x16_bf16 v[16:31], v[186:189], v[72:75], v[16:31]
	v_exp_f32_e32 v65, v100
	v_exp_f32_e32 v66, v101
	v_add_f32_e32 v64, v65, v64
	v_cvt_pk_bf16_f32 v94, v65, v66
	v_add_f32_e32 v64, v66, v64
	v_mfma_f32_32x32x16_bf16 v[0:15], v[190:193], v[164:167], v[0:15]
	v_exp_f32_e32 v65, v102
	v_exp_f32_e32 v66, v103
	v_add_f32_e32 v64, v65, v64
	v_cvt_pk_bf16_f32 v95, v65, v66
	v_add_f32_e32 v198, v66, v64
	s_mulk_i32 s8, 0x4800
	v_mfma_f32_32x32x16_bf16 v[0:15], v[194:197], v[72:75], v[0:15]
	v_add_u32_e32 v185, s8, v184
	ds_read_b128 v[64:67], v185
	ds_read_b128 v[100:103], v185 offset:32
	ds_read_b128 v[104:107], v185 offset:64
	v_cmp_nge_f32_e64 s[4:5], s62, v198
	ds_read_b128 v[108:111], v185 offset:96
	s_or_b64 s[6:7], s[6:7], vcc
	v_exp_f32_e32 v68, v76
	v_exp_f32_e32 v69, v77
	v_add_f32_e32 v70, 0, v68
	v_add_f32_e32 v97, v69, v70
	v_cvt_pk_bf16_f32 v96, v68, v69
	v_exp_f32_e32 v98, v78
	v_exp_f32_e32 v99, v79
	s_waitcnt lgkmcnt(3)
	v_mfma_f32_32x32x16_bf16 v[64:79], v[64:67], v[116:119], 0
	ds_read_b128 v[164:167], v168 offset:27712
	ds_read_b128 v[178:181], v168 offset:27744
	ds_read_b128 v[186:189], v168 offset:32320
	ds_read_b128 v[190:193], v168 offset:32352
	v_add_f32_e32 v97, v98, v97
	v_add_f32_e32 v168, v99, v97
	v_cvt_pk_bf16_f32 v97, v98, v99
	s_waitcnt lgkmcnt(5)
	v_mfma_f32_32x32x16_bf16 v[64:79], v[100:103], v[120:123], v[64:79]
	v_exp_f32_e32 v80, v80
	v_exp_f32_e32 v81, v81
	v_add_f32_e32 v99, v80, v168
	v_cvt_pk_bf16_f32 v98, v80, v81
	v_add_f32_e32 v80, v81, v99
	v_mfma_f32_32x32x16_bf16 v[64:79], v[104:107], v[124:127], v[64:79]
	v_exp_f32_e32 v81, v82
	v_exp_f32_e32 v82, v83
	v_add_f32_e32 v80, v81, v80
	v_cvt_pk_bf16_f32 v99, v81, v82
	v_add_f32_e32 v80, v82, v80
	s_waitcnt lgkmcnt(4)
	v_mfma_f32_32x32x16_bf16 v[64:79], v[108:111], v[128:131], v[64:79]
	v_exp_f32_e32 v81, v84
	v_exp_f32_e32 v82, v85
	v_add_f32_e32 v80, v81, v80
	v_cvt_pk_bf16_f32 v100, v81, v82
	v_add_f32_e32 v80, v82, v80
	s_waitcnt lgkmcnt(0)
	v_mfma_f32_32x32x16_bf16 v[48:63], v[164:167], v[112:115], v[48:63]
	v_exp_f32_e32 v81, v86
	v_exp_f32_e32 v82, v87
	v_add_f32_e32 v80, v81, v80
	v_cvt_pk_bf16_f32 v101, v81, v82
	v_add_f32_e32 v80, v82, v80
	v_mfma_f32_32x32x16_bf16 v[48:63], v[178:181], v[92:95], v[48:63]
	v_exp_f32_e32 v81, v88
	v_exp_f32_e32 v82, v89
	v_add_f32_e32 v80, v81, v80
	v_cvt_pk_bf16_f32 v102, v81, v82
	v_add_f32_e32 v80, v82, v80
	v_mfma_f32_32x32x16_bf16 v[32:47], v[186:189], v[112:115], v[32:47]
	v_exp_f32_e32 v81, v90
	v_exp_f32_e32 v82, v91
	v_add_f32_e32 v80, v81, v80
	v_cvt_pk_bf16_f32 v103, v81, v82
	v_add_f32_e32 v199, v82, v80
	v_mfma_f32_32x32x16_bf16 v[32:47], v[190:193], v[92:95], v[32:47]
	ds_read_b128 v[80:83], v185
	ds_read_b128 v[108:111], v185 offset:32
	ds_read_b128 v[104:107], v185 offset:64
	s_or_b64 s[4:5], s[6:7], s[4:5]
	v_cmp_nge_f32_e32 vcc, s62, v199
	s_or_b64 s[4:5], s[4:5], vcc
	s_cmp_lg_u64 s[4:5], 0
	s_cselect_b64 s[4:5], -1, 0
	s_or_b64 s[42:43], s[42:43], s[4:5]
	v_pk_add_f32 v[178:179], v[182:183], v[198:199]
	s_waitcnt lgkmcnt(0)
	s_barrier
	s_add_u32 s46, s46, 0x8000
	s_addc_u32 s47, s47, 0
	s_and_b64 vcc, exec, s[44:45]
	s_cbranch_vccnz .LBB0_451
	s_mov_b32 s33, s14
	s_branch .LBB0_437

.LBB0_927:
	s_add_i32 s6, s61, -1
	s_and_b32 s77, s61, 2
	s_and_b32 s79, s6, 3
	s_cmp_eq_u32 s61, 0
	s_cselect_b64 s[8:9], -1, 0
	s_mulk_i32 s79, 0x5800
	s_and_b64 s[6:7], s[8:9], exec
	s_mul_i32 s78, s77, 0x5800
	s_cselect_b32 s6, 0, s79
	s_add_i32 s76, s78, 0
	v_add_u32_e32 v199, s76, v241
	v_add_u32_e32 v210, s6, v244
	v_exp_f32_e32 v64, v64
	v_exp_f32_e32 v65, v65
	v_add_f32_e32 v84, 0, v64
	v_add_f32_e32 v84, v65, v84
	v_cvt_pk_bf16_f32 v178, v64, v65
	v_exp_f32_e32 v64, v66
	ds_read_b128 v[182:185], v199 offset:96
	ds_read_b128 v[246:249], v199 offset:128
	ds_read_b128 v[250:253], v199 offset:160
	v_exp_f32_e32 v65, v67
	v_add_f32_e32 v66, v64, v84
	s_waitcnt lgkmcnt(4)
	v_mfma_f32_32x32x16_bf16 v[80:95], v[80:83], v[122:125], 0
	v_add_f32_e32 v66, v65, v66
	v_cvt_pk_bf16_f32 v179, v64, v65
	v_mfma_f32_32x32x16_bf16 v[80:95], v[174:177], v[126:129], v[80:95]
	v_exp_f32_e32 v64, v68
	v_exp_f32_e32 v65, v69
	v_add_f32_e32 v66, v64, v66
	v_add_f32_e32 v66, v65, v66
	v_cvt_pk_bf16_f32 v180, v64, v65
	s_waitcnt lgkmcnt(3)
	v_mfma_f32_32x32x16_bf16 v[80:95], v[170:173], v[130:133], v[80:95]
	v_exp_f32_e32 v64, v70
	v_exp_f32_e32 v65, v71
	v_add_f32_e32 v66, v64, v66
	v_add_f32_e32 v170, v65, v66
	v_cvt_pk_bf16_f32 v181, v64, v65
	s_waitcnt lgkmcnt(2)
	v_mfma_f32_32x32x16_bf16 v[80:95], v[182:185], v[134:137], v[80:95]
	ds_read_b128 v[64:67], v210 offset:13376
	ds_read_b128 v[68:71], v210 offset:13408
	ds_read_b128 v[174:177], v210 offset:17984
	ds_read_b128 v[218:221], v210 offset:18016
	v_exp_f32_e32 v72, v72
	v_exp_f32_e32 v73, v73
	v_add_f32_e32 v170, v72, v170
	v_add_f32_e32 v171, v73, v170
	v_cvt_pk_bf16_f32 v170, v72, v73
	s_waitcnt lgkmcnt(4)
	v_mfma_f32_32x32x16_bf16 v[80:95], v[246:249], v[154:157], v[80:95]
	v_exp_f32_e32 v72, v74
	v_exp_f32_e32 v73, v75
	v_add_f32_e32 v74, v72, v171
	v_add_f32_e32 v74, v73, v74
	v_cvt_pk_bf16_f32 v171, v72, v73
	v_mfma_f32_32x32x16_bf16 v[80:95], v[250:253], v[158:161], v[80:95]
	v_exp_f32_e32 v72, v76
	v_exp_f32_e32 v73, v77
	v_add_f32_e32 v74, v72, v74
	v_add_f32_e32 v74, v73, v74
	v_cvt_pk_bf16_f32 v172, v72, v73
	s_waitcnt lgkmcnt(1)
	v_mfma_f32_32x32x16_bf16 v[16:31], v[64:67], v[162:165], v[16:31]
	v_exp_f32_e32 v64, v78
	v_exp_f32_e32 v65, v79
	v_add_f32_e32 v66, v64, v74
	v_add_f32_e32 v246, v65, v66
	v_cvt_pk_bf16_f32 v173, v64, v65
	v_mfma_f32_32x32x16_bf16 v[0:15], v[174:177], v[162:165], v[0:15]
	ds_read_b128 v[64:67], v199 offset:6656
	ds_read_b128 v[182:185], v199 offset:6688
	ds_read_b128 v[174:177], v199 offset:6720
	v_cmp_ge_f32_e32 vcc, s48, v246
	s_mov_b64 s[10:11], -1
	s_mov_b64 s[6:7], -1
	v_mfma_f32_32x32x16_bf16 v[16:31], v[68:71], v[166:169], v[16:31]
	s_waitcnt lgkmcnt(3)
	v_mfma_f32_32x32x16_bf16 v[0:15], v[218:221], v[166:169], v[0:15]
	s_and_saveexec_b64 s[12:13], vcc
	v_cmp_gt_f32_e32 vcc, s49, v246
	s_and_b64 s[6:7], s[8:9], vcc
	s_orn2_b64 s[6:7], s[6:7], exec
	s_or_b64 exec, exec, s[12:13]
	v_add_u32_e32 v211, s76, v243
	v_exp_f32_e32 v68, v80
	v_exp_f32_e32 v69, v81
	v_add_f32_e32 v70, 0, v68
	v_add_f32_e32 v70, v69, v70
	v_cvt_pk_bf16_f32 v162, v68, v69
	v_exp_f32_e32 v80, v82
	ds_read_b128 v[166:169], v199 offset:6752
	ds_read_b128 v[218:221], v199 offset:6784
	ds_read_b128 v[248:251], v199 offset:6816
	v_exp_f32_e32 v81, v83
	v_add_f32_e32 v82, v80, v70
	s_waitcnt lgkmcnt(3)
	v_mfma_f32_32x32x16_bf16 v[64:79], v[64:67], v[98:101], 0
	v_add_f32_e32 v82, v81, v82
	v_cvt_pk_bf16_f32 v163, v80, v81
	v_mfma_f32_32x32x16_bf16 v[64:79], v[182:185], v[102:105], v[64:79]
	v_exp_f32_e32 v80, v84
	v_exp_f32_e32 v81, v85
	v_add_f32_e32 v82, v80, v82
	v_add_f32_e32 v82, v81, v82
	v_cvt_pk_bf16_f32 v164, v80, v81
	v_mfma_f32_32x32x16_bf16 v[64:79], v[174:177], v[106:109], v[64:79]
	v_exp_f32_e32 v80, v86
	v_exp_f32_e32 v81, v87
	v_add_f32_e32 v82, v80, v82
	v_add_f32_e32 v174, v81, v82
	v_cvt_pk_bf16_f32 v165, v80, v81
	s_waitcnt lgkmcnt(2)
	v_mfma_f32_32x32x16_bf16 v[64:79], v[166:169], v[110:113], v[64:79]
	ds_read_b128 v[80:83], v211 offset:13312
	ds_read_b128 v[84:87], v211 offset:13344
	ds_read_b128 v[182:185], v211 offset:17920
	ds_read_b128 v[222:225], v211 offset:17952
	v_exp_f32_e32 v88, v88
	v_exp_f32_e32 v89, v89
	v_add_f32_e32 v166, v88, v174
	v_add_f32_e32 v166, v89, v166
	v_cvt_pk_bf16_f32 v174, v88, v89
	s_waitcnt lgkmcnt(4)
	v_mfma_f32_32x32x16_bf16 v[64:79], v[218:221], v[114:117], v[64:79]
	v_exp_f32_e32 v88, v90
	v_exp_f32_e32 v89, v91
	v_add_f32_e32 v90, v88, v166
	v_add_f32_e32 v90, v89, v90
	v_cvt_pk_bf16_f32 v175, v88, v89
	v_mfma_f32_32x32x16_bf16 v[64:79], v[248:251], v[118:121], v[64:79]
	v_exp_f32_e32 v88, v92
	v_exp_f32_e32 v89, v93
	v_add_f32_e32 v90, v88, v90
	v_add_f32_e32 v90, v89, v90
	v_cvt_pk_bf16_f32 v176, v88, v89
	s_waitcnt lgkmcnt(1)
	v_mfma_f32_32x32x16_bf16 v[48:63], v[80:83], v[178:181], v[48:63]
	v_exp_f32_e32 v80, v94
	v_exp_f32_e32 v81, v95
	v_add_f32_e32 v82, v80, v90
	v_add_f32_e32 v247, v81, v82
	v_cvt_pk_bf16_f32 v177, v80, v81
	v_mfma_f32_32x32x16_bf16 v[32:47], v[182:185], v[178:181], v[32:47]
	ds_read_b128 v[80:83], v199 offset:6656
	ds_read_b128 v[182:185], v199 offset:6688
	ds_read_b128 v[178:181], v199 offset:6720
	v_cmp_ge_f32_e32 vcc, s48, v247
	v_mfma_f32_32x32x16_bf16 v[48:63], v[84:87], v[170:173], v[48:63]
	v_cndmask_b32_e64 v84, 0, 1, s[6:7]
	v_cmp_ne_u32_e64 s[6:7], 0, v84
	s_waitcnt lgkmcnt(3)
	v_mfma_f32_32x32x16_bf16 v[32:47], v[222:225], v[170:173], v[32:47]
	s_and_saveexec_b64 s[12:13], vcc
	v_cmp_gt_f32_e32 vcc, s49, v247
	s_and_b64 s[8:9], s[8:9], vcc
	s_orn2_b64 s[10:11], s[8:9], exec
	s_or_b64 exec, exec, s[12:13]
	v_cndmask_b32_e64 v84, 0, 1, s[10:11]
	v_cmp_ne_u32_e64 s[8:9], 0, v84
	v_exp_f32_e32 v64, v64
	v_exp_f32_e32 v65, v65
	v_add_f32_e32 v84, 0, v64
	v_add_f32_e32 v84, v65, v84
	v_cvt_pk_bf16_f32 v166, v64, v65
	v_exp_f32_e32 v64, v66
	ds_read_b128 v[170:173], v199 offset:6752
	ds_read_b128 v[218:221], v199 offset:6784
	ds_read_b128 v[222:225], v199 offset:6816
	v_exp_f32_e32 v65, v67
	v_add_f32_e32 v66, v64, v84
	s_waitcnt lgkmcnt(3)
	v_mfma_f32_32x32x16_bf16 v[80:95], v[80:83], v[122:125], 0
	v_add_f32_e32 v66, v65, v66
	v_cvt_pk_bf16_f32 v167, v64, v65
	v_mfma_f32_32x32x16_bf16 v[80:95], v[182:185], v[126:129], v[80:95]
	v_exp_f32_e32 v64, v68
	v_exp_f32_e32 v65, v69
	v_add_f32_e32 v66, v64, v66
	v_add_f32_e32 v66, v65, v66
	v_cvt_pk_bf16_f32 v168, v64, v65
	v_mfma_f32_32x32x16_bf16 v[80:95], v[178:181], v[130:133], v[80:95]
	v_exp_f32_e32 v64, v70
	v_exp_f32_e32 v65, v71
	v_add_f32_e32 v66, v64, v66
	v_add_f32_e32 v178, v65, v66
	v_cvt_pk_bf16_f32 v169, v64, v65
	s_waitcnt lgkmcnt(2)
	v_mfma_f32_32x32x16_bf16 v[80:95], v[170:173], v[134:137], v[80:95]
	ds_read_b128 v[64:67], v211 offset:13312
	ds_read_b128 v[68:71], v211 offset:13344
	ds_read_b128 v[182:185], v211 offset:17920
	ds_read_b128 v[248:251], v211 offset:17952
	v_exp_f32_e32 v72, v72
	v_exp_f32_e32 v73, v73
	v_add_f32_e32 v170, v72, v178
	v_add_f32_e32 v170, v73, v170
	v_cvt_pk_bf16_f32 v178, v72, v73
	s_waitcnt lgkmcnt(4)
	v_mfma_f32_32x32x16_bf16 v[80:95], v[218:221], v[154:157], v[80:95]
	v_exp_f32_e32 v72, v74
	v_exp_f32_e32 v73, v75
	v_add_f32_e32 v74, v72, v170
	v_add_f32_e32 v74, v73, v74
	v_cvt_pk_bf16_f32 v179, v72, v73
	v_mfma_f32_32x32x16_bf16 v[80:95], v[222:225], v[158:161], v[80:95]
	v_exp_f32_e32 v72, v76
	v_exp_f32_e32 v73, v77
	v_add_f32_e32 v74, v72, v74
	v_add_f32_e32 v74, v73, v74
	v_cvt_pk_bf16_f32 v180, v72, v73
	s_waitcnt lgkmcnt(1)
	v_mfma_f32_32x32x16_bf16 v[16:31], v[64:67], v[162:165], v[16:31]
	v_exp_f32_e32 v64, v78
	v_exp_f32_e32 v65, v79
	v_add_f32_e32 v66, v64, v74
	v_add_f32_e32 v210, v65, v66
	v_cvt_pk_bf16_f32 v181, v64, v65
	v_mfma_f32_32x32x16_bf16 v[0:15], v[182:185], v[162:165], v[0:15]
	v_add_u32_e32 v226, s78, v242
	ds_read_b128 v[64:67], v226 offset:22528
	ds_read_b128 v[170:173], v226 offset:22560
	ds_read_b128 v[182:185], v226 offset:22592
	v_cmp_nge_f32_e64 s[10:11], s48, v210
	v_mfma_f32_32x32x16_bf16 v[16:31], v[68:71], v[174:177], v[16:31]
	s_waitcnt lgkmcnt(3)
	v_mfma_f32_32x32x16_bf16 v[0:15], v[248:251], v[174:177], v[0:15]
	v_exp_f32_e32 v68, v80
	v_exp_f32_e32 v69, v81
	v_add_f32_e32 v70, 0, v68
	v_add_f32_e32 v70, v69, v70
	v_cvt_pk_bf16_f32 v162, v68, v69
	v_exp_f32_e32 v80, v82
	ds_read_b128 v[174:177], v226 offset:22624
	ds_read_b128 v[218:221], v226 offset:22656
	ds_read_b128 v[222:225], v226 offset:22688
	v_exp_f32_e32 v81, v83
	v_add_f32_e32 v82, v80, v70
	s_waitcnt lgkmcnt(3)
	v_mfma_f32_32x32x16_bf16 v[64:79], v[64:67], v[98:101], 0
	v_add_f32_e32 v82, v81, v82
	v_cvt_pk_bf16_f32 v163, v80, v81
	v_mfma_f32_32x32x16_bf16 v[64:79], v[170:173], v[102:105], v[64:79]
	v_exp_f32_e32 v80, v84
	v_exp_f32_e32 v81, v85
	v_add_f32_e32 v82, v80, v82
	v_add_f32_e32 v82, v81, v82
	v_cvt_pk_bf16_f32 v164, v80, v81
	v_mfma_f32_32x32x16_bf16 v[64:79], v[182:185], v[106:109], v[64:79]
	v_exp_f32_e32 v80, v86
	v_exp_f32_e32 v81, v87
	v_add_f32_e32 v82, v80, v82
	v_add_f32_e32 v170, v81, v82
	v_cvt_pk_bf16_f32 v165, v80, v81
	s_waitcnt lgkmcnt(2)
	v_mfma_f32_32x32x16_bf16 v[64:79], v[174:177], v[110:113], v[64:79]
	ds_read_b128 v[80:83], v211 offset:13376
	ds_read_b128 v[84:87], v211 offset:13408
	ds_read_b128 v[182:185], v211 offset:17984
	ds_read_b128 v[248:251], v211 offset:18016
	v_exp_f32_e32 v88, v88
	v_exp_f32_e32 v89, v89
	v_add_f32_e32 v170, v88, v170
	v_add_f32_e32 v171, v89, v170
	v_cvt_pk_bf16_f32 v170, v88, v89
	s_waitcnt lgkmcnt(4)
	v_mfma_f32_32x32x16_bf16 v[64:79], v[218:221], v[114:117], v[64:79]
	v_exp_f32_e32 v88, v90
	v_exp_f32_e32 v89, v91
	v_add_f32_e32 v90, v88, v171
	v_add_f32_e32 v90, v89, v90
	v_cvt_pk_bf16_f32 v171, v88, v89
	v_mfma_f32_32x32x16_bf16 v[64:79], v[222:225], v[118:121], v[64:79]
	v_exp_f32_e32 v88, v92
	v_exp_f32_e32 v89, v93
	v_add_f32_e32 v90, v88, v90
	v_add_f32_e32 v90, v89, v90
	v_cvt_pk_bf16_f32 v172, v88, v89
	s_waitcnt lgkmcnt(1)
	v_mfma_f32_32x32x16_bf16 v[48:63], v[80:83], v[166:169], v[48:63]
	v_exp_f32_e32 v80, v94
	v_exp_f32_e32 v81, v95
	v_add_f32_e32 v82, v80, v90
	v_add_f32_e32 v211, v81, v82
	v_cvt_pk_bf16_f32 v173, v80, v81
	v_mfma_f32_32x32x16_bf16 v[32:47], v[182:185], v[166:169], v[32:47]
	ds_read_b128 v[80:83], v226 offset:22528
	ds_read_b128 v[182:185], v226 offset:22560
	ds_read_b128 v[174:177], v226 offset:22592
	v_cmp_nge_f32_e64 s[12:13], s48, v211
	v_mfma_f32_32x32x16_bf16 v[48:63], v[84:87], v[178:181], v[48:63]
	s_waitcnt lgkmcnt(3)
	v_mfma_f32_32x32x16_bf16 v[32:47], v[248:251], v[178:181], v[32:47]
	s_waitcnt lgkmcnt(0)
	s_barrier
	s_cmpk_gt_u32 s61, 0xfc
	s_cbranch_scc1 .LBB0_933
	s_add_i32 s24, s79, 0
	v_add_u32_e32 v84, s24, v238
	v_add_u32_e32 v85, s24, v245
	v_add_u32_e32 v86, s24, v198
	s_waitcnt vmcnt(1)
	ds_write_b128 v84, v[150:153]
	s_waitcnt vmcnt(0)
	ds_write_b64 v85, v[190:191] offset:128
	ds_write_b128 v86, v[138:141] offset:13312

.LBB0_935:
	s_or_b64 s[6:7], s[8:9], s[6:7]
	v_add_f32_e32 v84, v204, v246
	v_add_f32_e32 v85, v205, v247
	s_or_b64 s[6:7], s[6:7], s[10:11]
	s_or_b64 s[6:7], s[6:7], s[12:13]
	v_pk_add_f32 v[178:179], v[84:85], v[210:211]
	s_xor_b32 s10, s77, 2
	v_add_u32_e32 v222, s78, v244
	v_exp_f32_e32 v64, v64
	v_exp_f32_e32 v65, v65
	v_add_f32_e32 v84, 0, v64
	v_add_f32_e32 v84, v65, v84
	v_cvt_pk_bf16_f32 v166, v64, v65
	v_exp_f32_e32 v64, v66
	ds_read_b128 v[204:207], v199 offset:22624
	ds_read_b128 v[208:211], v199 offset:22656
	ds_read_b128 v[218:221], v199 offset:22688
	v_exp_f32_e32 v65, v67
	v_add_f32_e32 v66, v64, v84
	s_waitcnt lgkmcnt(5)
	v_mfma_f32_32x32x16_bf16 v[80:95], v[80:83], v[122:125], 0
	v_add_f32_e32 v66, v65, v66
	v_cvt_pk_bf16_f32 v167, v64, v65
	s_waitcnt lgkmcnt(3)
	v_mfma_f32_32x32x16_bf16 v[80:95], v[182:185], v[126:129], v[80:95]
	v_exp_f32_e32 v64, v68
	v_exp_f32_e32 v65, v69
	v_add_f32_e32 v66, v64, v66
	v_add_f32_e32 v66, v65, v66
	v_cvt_pk_bf16_f32 v168, v64, v65
	v_mfma_f32_32x32x16_bf16 v[80:95], v[174:177], v[130:133], v[80:95]
	v_exp_f32_e32 v64, v70
	v_exp_f32_e32 v65, v71
	v_add_f32_e32 v66, v64, v66
	v_add_f32_e32 v174, v65, v66
	v_cvt_pk_bf16_f32 v169, v64, v65
	s_waitcnt lgkmcnt(2)
	v_mfma_f32_32x32x16_bf16 v[80:95], v[204:207], v[134:137], v[80:95]
	ds_read_b128 v[64:67], v222 offset:13376
	ds_read_b128 v[68:71], v222 offset:13408
	ds_read_b128 v[180:183], v222 offset:17984
	ds_read_b128 v[222:225], v222 offset:18016
	v_exp_f32_e32 v72, v72
	v_exp_f32_e32 v73, v73
	v_add_f32_e32 v174, v72, v174
	v_add_f32_e32 v175, v73, v174
	v_cvt_pk_bf16_f32 v174, v72, v73
	s_waitcnt lgkmcnt(4)
	v_mfma_f32_32x32x16_bf16 v[80:95], v[208:211], v[154:157], v[80:95]
	v_exp_f32_e32 v72, v74
	v_exp_f32_e32 v73, v75
	v_add_f32_e32 v74, v72, v175
	v_add_f32_e32 v74, v73, v74
	v_cvt_pk_bf16_f32 v175, v72, v73
	v_mfma_f32_32x32x16_bf16 v[80:95], v[218:221], v[158:161], v[80:95]
	v_exp_f32_e32 v72, v76
	v_exp_f32_e32 v73, v77
	v_add_f32_e32 v74, v72, v74
	v_add_f32_e32 v74, v73, v74
	v_cvt_pk_bf16_f32 v176, v72, v73
	s_waitcnt lgkmcnt(1)
	v_mfma_f32_32x32x16_bf16 v[16:31], v[64:67], v[162:165], v[16:31]
	v_exp_f32_e32 v64, v78
	v_exp_f32_e32 v65, v79
	v_add_f32_e32 v66, v64, v74
	v_add_f32_e32 v204, v65, v66
	v_cvt_pk_bf16_f32 v177, v64, v65
	v_mfma_f32_32x32x16_bf16 v[0:15], v[180:183], v[162:165], v[0:15]
	ds_read_b128 v[64:67], v199 offset:29184
	ds_read_b128 v[180:183], v199 offset:29216
	ds_read_b128 v[208:211], v199 offset:29248
	v_cmp_nge_f32_e32 vcc, s48, v204
	v_mfma_f32_32x32x16_bf16 v[16:31], v[68:71], v[170:173], v[16:31]
	s_waitcnt lgkmcnt(3)
	v_mfma_f32_32x32x16_bf16 v[0:15], v[222:225], v[170:173], v[0:15]
	v_mad_u32_u24 v68, v187, s69, v186
	v_add_u32_e32 v206, s76, v68
	v_exp_f32_e32 v68, v80
	v_exp_f32_e32 v69, v81
	v_add_f32_e32 v70, 0, v68
	v_add_f32_e32 v70, v69, v70
	v_cvt_pk_bf16_f32 v162, v68, v69
	v_exp_f32_e32 v80, v82
	ds_read_b128 v[170:173], v199 offset:29280
	ds_read_b128 v[218:221], v199 offset:29312
	ds_read_b128 v[222:225], v199 offset:29344
	v_exp_f32_e32 v81, v83
	v_add_f32_e32 v82, v80, v70
	s_waitcnt lgkmcnt(3)
	v_mfma_f32_32x32x16_bf16 v[64:79], v[64:67], v[98:101], 0
	v_add_f32_e32 v82, v81, v82
	v_cvt_pk_bf16_f32 v163, v80, v81
	v_mfma_f32_32x32x16_bf16 v[64:79], v[180:183], v[102:105], v[64:79]
	v_exp_f32_e32 v80, v84
	v_exp_f32_e32 v81, v85
	v_add_f32_e32 v82, v80, v82
	v_add_f32_e32 v82, v81, v82
	v_cvt_pk_bf16_f32 v164, v80, v81
	v_mfma_f32_32x32x16_bf16 v[64:79], v[208:211], v[106:109], v[64:79]
	v_exp_f32_e32 v80, v86
	v_exp_f32_e32 v81, v87
	v_add_f32_e32 v82, v80, v82
	v_add_f32_e32 v184, v81, v82
	v_cvt_pk_bf16_f32 v165, v80, v81
	s_waitcnt lgkmcnt(2)
	v_mfma_f32_32x32x16_bf16 v[64:79], v[170:173], v[110:113], v[64:79]
	ds_read_b128 v[80:83], v206 offset:35840
	ds_read_b128 v[84:87], v206 offset:35872
	ds_read_b128 v[180:183], v206 offset:40448
	ds_read_b128 v[208:211], v206 offset:40480
	v_exp_f32_e32 v88, v88
	v_exp_f32_e32 v89, v89
	v_add_f32_e32 v170, v88, v184
	v_add_f32_e32 v171, v89, v170
	v_cvt_pk_bf16_f32 v170, v88, v89
	s_waitcnt lgkmcnt(4)
	v_mfma_f32_32x32x16_bf16 v[64:79], v[218:221], v[114:117], v[64:79]
	v_exp_f32_e32 v88, v90
	v_exp_f32_e32 v89, v91
	v_add_f32_e32 v90, v88, v171
	v_add_f32_e32 v90, v89, v90
	v_cvt_pk_bf16_f32 v171, v88, v89
	v_mfma_f32_32x32x16_bf16 v[64:79], v[222:225], v[118:121], v[64:79]
	v_exp_f32_e32 v88, v92
	v_exp_f32_e32 v89, v93
	v_add_f32_e32 v90, v88, v90
	v_add_f32_e32 v90, v89, v90
	v_cvt_pk_bf16_f32 v172, v88, v89
	s_waitcnt lgkmcnt(1)
	v_mfma_f32_32x32x16_bf16 v[48:63], v[80:83], v[166:169], v[48:63]
	v_exp_f32_e32 v80, v94
	v_exp_f32_e32 v81, v95
	v_add_f32_e32 v82, v80, v90
	v_add_f32_e32 v205, v81, v82
	v_cvt_pk_bf16_f32 v173, v80, v81
	v_mfma_f32_32x32x16_bf16 v[32:47], v[180:183], v[166:169], v[32:47]
	ds_read_b128 v[80:83], v199 offset:29184
	ds_read_b128 v[166:169], v199 offset:29216
	ds_read_b128 v[182:185], v199 offset:29248
	s_or_b64 s[8:9], s[6:7], vcc
	v_cmp_nge_f32_e32 vcc, s48, v205
	v_pk_add_f32 v[204:205], v[178:179], v[204:205]
	v_mfma_f32_32x32x16_bf16 v[48:63], v[84:87], v[174:177], v[48:63]
	s_waitcnt lgkmcnt(3)
	v_mfma_f32_32x32x16_bf16 v[32:47], v[208:211], v[174:177], v[32:47]
	v_exp_f32_e32 v64, v64
	v_exp_f32_e32 v65, v65
	v_add_f32_e32 v84, 0, v64
	v_add_f32_e32 v84, v65, v84
	v_cvt_pk_bf16_f32 v178, v64, v65
	v_exp_f32_e32 v64, v66
	ds_read_b128 v[174:177], v199 offset:29280
	ds_read_b128 v[208:211], v199 offset:29312
	ds_read_b128 v[218:221], v199 offset:29344
	v_exp_f32_e32 v65, v67
	v_add_f32_e32 v66, v64, v84
	s_waitcnt lgkmcnt(3)
	v_mfma_f32_32x32x16_bf16 v[80:95], v[80:83], v[122:125], 0
	v_add_f32_e32 v66, v65, v66
	v_cvt_pk_bf16_f32 v179, v64, v65
	v_mfma_f32_32x32x16_bf16 v[80:95], v[166:169], v[126:129], v[80:95]
	v_exp_f32_e32 v64, v68
	v_exp_f32_e32 v65, v69
	v_add_f32_e32 v66, v64, v66
	v_add_f32_e32 v66, v65, v66
	v_cvt_pk_bf16_f32 v180, v64, v65
	v_mfma_f32_32x32x16_bf16 v[80:95], v[182:185], v[130:133], v[80:95]
	v_exp_f32_e32 v64, v70
	v_exp_f32_e32 v65, v71
	v_add_f32_e32 v66, v64, v66
	v_add_f32_e32 v182, v65, v66
	v_cvt_pk_bf16_f32 v181, v64, v65
	s_waitcnt lgkmcnt(2)
	v_mfma_f32_32x32x16_bf16 v[80:95], v[174:177], v[134:137], v[80:95]
	ds_read_b128 v[64:67], v206 offset:35840
	ds_read_b128 v[68:71], v206 offset:35872
	ds_read_b128 v[166:169], v206 offset:40448
	ds_read_b128 v[222:225], v206 offset:40480
	v_exp_f32_e32 v72, v72
	v_exp_f32_e32 v73, v73
	v_add_f32_e32 v174, v72, v182
	v_add_f32_e32 v174, v73, v174
	v_cvt_pk_bf16_f32 v182, v72, v73
	s_waitcnt lgkmcnt(4)
	v_mfma_f32_32x32x16_bf16 v[80:95], v[208:211], v[154:157], v[80:95]
	v_exp_f32_e32 v72, v74
	v_exp_f32_e32 v73, v75
	v_add_f32_e32 v74, v72, v174
	v_add_f32_e32 v74, v73, v74
	v_cvt_pk_bf16_f32 v183, v72, v73
	v_mfma_f32_32x32x16_bf16 v[80:95], v[218:221], v[158:161], v[80:95]
	v_exp_f32_e32 v72, v76
	v_exp_f32_e32 v73, v77
	v_add_f32_e32 v74, v72, v74
	v_add_f32_e32 v74, v73, v74
	v_cvt_pk_bf16_f32 v184, v72, v73
	s_waitcnt lgkmcnt(1)
	v_mfma_f32_32x32x16_bf16 v[16:31], v[64:67], v[162:165], v[16:31]
	v_exp_f32_e32 v64, v78
	v_exp_f32_e32 v65, v79
	v_add_f32_e32 v66, v64, v74
	v_add_f32_e32 v226, v65, v66
	v_cvt_pk_bf16_f32 v185, v64, v65
	v_mfma_f32_32x32x16_bf16 v[0:15], v[166:169], v[162:165], v[0:15]
	s_mulk_i32 s10, 0x5800
	v_add_u32_e32 v199, s10, v242
	ds_read_b128 v[64:67], v199
	ds_read_b128 v[164:167], v199 offset:32
	ds_read_b128 v[174:177], v199 offset:64
	v_cmp_nge_f32_e64 s[6:7], s48, v226
	v_mfma_f32_32x32x16_bf16 v[16:31], v[68:71], v[170:173], v[16:31]
	s_waitcnt lgkmcnt(3)
	v_mfma_f32_32x32x16_bf16 v[0:15], v[222:225], v[170:173], v[0:15]
	s_or_b64 s[8:9], s[8:9], vcc
	v_exp_f32_e32 v68, v80
	v_exp_f32_e32 v69, v81
	v_add_f32_e32 v70, 0, v68
	v_add_f32_e32 v70, v69, v70
	v_cvt_pk_bf16_f32 v162, v68, v69
	v_exp_f32_e32 v80, v82
	ds_read_b128 v[168:171], v199 offset:96
	ds_read_b128 v[208:211], v199 offset:128
	ds_read_b128 v[218:221], v199 offset:160
	v_exp_f32_e32 v81, v83
	v_add_f32_e32 v82, v80, v70
	s_waitcnt lgkmcnt(3)
	v_mfma_f32_32x32x16_bf16 v[64:79], v[64:67], v[98:101], 0
	v_add_f32_e32 v82, v81, v82
	v_cvt_pk_bf16_f32 v163, v80, v81
	v_mfma_f32_32x32x16_bf16 v[64:79], v[164:167], v[102:105], v[64:79]
	v_exp_f32_e32 v80, v84
	v_exp_f32_e32 v81, v85
	v_add_f32_e32 v82, v80, v82
	v_add_f32_e32 v82, v81, v82
	v_cvt_pk_bf16_f32 v164, v80, v81
	v_mfma_f32_32x32x16_bf16 v[64:79], v[174:177], v[106:109], v[64:79]
	v_exp_f32_e32 v80, v86
	v_exp_f32_e32 v81, v87
	v_add_f32_e32 v82, v80, v82
	v_add_f32_e32 v166, v81, v82
	v_cvt_pk_bf16_f32 v165, v80, v81
	s_waitcnt lgkmcnt(2)
	v_mfma_f32_32x32x16_bf16 v[64:79], v[168:171], v[110:113], v[64:79]
	ds_read_b128 v[80:83], v206 offset:35904
	ds_read_b128 v[84:87], v206 offset:35936
	ds_read_b128 v[222:225], v206 offset:40512
	ds_read_b128 v[246:249], v206 offset:40544
	v_exp_f32_e32 v88, v88
	v_exp_f32_e32 v89, v89
	v_add_f32_e32 v166, v88, v166
	v_add_f32_e32 v167, v89, v166
	v_cvt_pk_bf16_f32 v166, v88, v89
	s_waitcnt lgkmcnt(4)
	v_mfma_f32_32x32x16_bf16 v[64:79], v[208:211], v[114:117], v[64:79]
	v_exp_f32_e32 v88, v90
	v_exp_f32_e32 v89, v91
	v_add_f32_e32 v90, v88, v167
	v_add_f32_e32 v90, v89, v90
	v_cvt_pk_bf16_f32 v167, v88, v89
	v_mfma_f32_32x32x16_bf16 v[64:79], v[218:221], v[118:121], v[64:79]
	v_exp_f32_e32 v88, v92
	v_exp_f32_e32 v89, v93
	v_add_f32_e32 v90, v88, v90
	v_add_f32_e32 v90, v89, v90
	v_cvt_pk_bf16_f32 v168, v88, v89
	s_waitcnt lgkmcnt(1)
	v_mfma_f32_32x32x16_bf16 v[48:63], v[80:83], v[178:181], v[48:63]
	v_exp_f32_e32 v80, v94
	v_exp_f32_e32 v81, v95
	v_add_f32_e32 v82, v80, v90
	v_add_f32_e32 v227, v81, v82
	v_cvt_pk_bf16_f32 v169, v80, v81
	v_mfma_f32_32x32x16_bf16 v[32:47], v[222:225], v[178:181], v[32:47]
	ds_read_b128 v[80:83], v199
	ds_read_b128 v[174:177], v199 offset:32
	ds_read_b128 v[170:173], v199 offset:64
	s_or_b64 s[6:7], s[8:9], s[6:7]
	v_cmp_nge_f32_e32 vcc, s48, v227
	s_or_b64 s[6:7], s[6:7], vcc
	s_cmp_lg_u64 s[6:7], 0
	s_cselect_b64 s[6:7], -1, 0
	s_or_b64 s[42:43], s[42:43], s[6:7]
	v_mfma_f32_32x32x16_bf16 v[48:63], v[84:87], v[182:185], v[48:63]
	v_add_f32_e64 v204, v204, v226
	v_add_f32_e64 v205, v205, v227
	s_waitcnt lgkmcnt(3)
	v_mfma_f32_32x32x16_bf16 v[32:47], v[246:249], v[182:185], v[32:47]
	s_waitcnt lgkmcnt(0)
	s_barrier
	s_add_u32 s40, s40, 0x40000
	s_mov_b64 s[6:7], 0x2000
	s_addc_u32 s41, s41, 0
	v_lshl_add_u64 v[202:203], v[202:203], 0, s[6:7]
	s_and_b64 vcc, exec, s[44:45]
	s_cbranch_vccnz .LBB0_937
	s_mov_b32 s61, s30
	s_branch .LBB0_923
